# final epilogue: residual rows of chunks 1-3 fetched ahead of the output stores (deeper load pipeline), output stores without nt
# baseline (speedup 1.0000x reference)
.LBB0_1466:
	v_lshl_or_b32 v128, s42, 8, v168
	v_lshl_add_u32 v164, s41, 8, v166
	s_ashr_i32 s16, s41, 5
	v_ashrrev_i32_e32 v129, 31, v128
	v_ashrrev_i32_e32 v165, 31, v164
	s_mul_hi_i32 s17, s16, 0x6000
	s_mulk_i32 s16, 0x6000
	v_or_b32_e32 v188, 16, v164
	v_lshl_add_u64 v[162:163], v[128:129], 1, s[10:11]
	v_lshlrev_b64 v[130:131], 11, v[164:165]
	s_add_u32 s16, s31, s16
	v_ashrrev_i32_e32 v189, 31, v188
	v_lshl_add_u64 v[130:131], v[162:163], 0, v[130:131]
	v_lshlrev_b64 v[160:161], 2, v[128:129]
	s_addc_u32 s17, s34, s17
	v_lshlrev_b64 v[180:181], 11, v[188:189]
	global_load_dwordx4 v[172:175], v[130:131], off nt
	global_load_dwordx4 v[176:179], v[130:131], off offset:256 nt
	v_mov_b32_e32 v252, v130
	v_mov_b32_e32 v253, v131
	s_mov_b32 s98, 0x10000
	s_mov_b32 s99, 0
	v_lshl_add_u64 v[248:249], s[98:99], 0, v[130:131]
	global_load_dwordx4 v[200:203], v[248:249], off nt
	global_load_dwordx4 v[204:207], v[248:249], off offset:256 nt
	s_nop 1
	s_mov_b32 s98, 0x18000
	s_mov_b32 s99, 0
	v_lshl_add_u64 v[248:249], s[98:99], 0, v[130:131]
	global_load_dwordx4 v[208:211], v[248:249], off nt
	global_load_dwordx4 v[212:215], v[248:249], off offset:256 nt
	s_nop 1
	s_mov_b32 s98, 0x40000
	s_mov_b32 s99, 0
	v_lshl_add_u64 v[248:249], s[98:99], 0, v[130:131]
	global_load_dwordx4 v[230:233], v[248:249], off nt
	global_load_dwordx4 v[234:237], v[248:249], off offset:256 nt
	s_nop 1
	s_mov_b32 s98, 0x48000
	s_mov_b32 s99, 0
	v_lshl_add_u64 v[248:249], s[98:99], 0, v[130:131]
	global_load_dwordx4 v[238:241], v[248:249], off nt
	global_load_dwordx4 v[244:247], v[248:249], off offset:256 nt
	s_nop 1
	v_lshl_add_u64 v[140:141], s[16:17], 0, v[160:161]
	v_lshl_add_u64 v[184:185], v[162:163], 0, v[180:181]
	global_load_dwordx4 v[136:139], v[140:141], off
	global_load_dwordx4 v[132:135], v[140:141], off offset:16
	global_load_dwordx4 v[128:131], v[140:141], off offset:528
	s_nop 0
	global_load_dwordx4 v[140:143], v[140:141], off offset:512
	s_nop 0
	global_load_dwordx4 v[180:183], v[184:185], off nt
	s_nop 0
	global_load_dwordx4 v[184:187], v[184:185], off offset:256 nt
	v_lshlrev_b64 v[190:191], 12, v[164:165]
	v_lshl_add_u64 v[190:191], s[82:83], 0, v[190:191]
	v_lshlrev_b64 v[188:189], 12, v[188:189]
	v_lshl_add_u64 v[190:191], v[190:191], 0, v[160:161]
	v_lshl_add_u64 v[188:189], s[82:83], 0, v[188:189]
	v_lshl_add_u64 v[188:189], v[188:189], 0, v[160:161]
	s_and_b64 vcc, exec, s[0:1]
	s_mov_b64 s[0:1], -1
	s_waitcnt vmcnt(0)
	v_lshlrev_b32_e32 v192, 16, v172
	v_and_b32_e32 v193, 0xffff0000, v172
	v_lshlrev_b32_e32 v172, 16, v173
	v_and_b32_e32 v173, 0xffff0000, v173
	v_lshlrev_b32_e32 v194, 16, v174
	v_and_b32_e32 v195, 0xffff0000, v174
	v_lshlrev_b32_e32 v174, 16, v175
	v_and_b32_e32 v175, 0xffff0000, v175
	v_lshlrev_b32_e32 v196, 16, v176
	v_and_b32_e32 v197, 0xffff0000, v176
	v_lshlrev_b32_e32 v176, 16, v177
	v_and_b32_e32 v177, 0xffff0000, v177
	v_lshlrev_b32_e32 v198, 16, v178
	v_and_b32_e32 v199, 0xffff0000, v178
	v_lshlrev_b32_e32 v178, 16, v179
	v_and_b32_e32 v179, 0xffff0000, v179
	v_pk_fma_f32 v[126:127], v[126:127], v[138:139], v[172:173]
	v_pk_fma_f32 v[124:125], v[124:125], v[136:137], v[192:193]
	v_pk_fma_f32 v[122:123], v[122:123], v[134:135], v[174:175]
	v_pk_fma_f32 v[114:115], v[114:115], v[142:143], v[176:177]
	v_pk_fma_f32 v[112:113], v[112:113], v[140:141], v[196:197]
	v_pk_fma_f32 v[106:107], v[106:107], v[130:131], v[178:179]
	v_lshlrev_b32_e32 v172, 16, v180
	v_and_b32_e32 v173, 0xffff0000, v180
	v_lshlrev_b32_e32 v174, 16, v181
	v_and_b32_e32 v175, 0xffff0000, v181
	v_lshlrev_b32_e32 v176, 16, v182
	v_and_b32_e32 v177, 0xffff0000, v182
	v_lshlrev_b32_e32 v178, 16, v183
	v_and_b32_e32 v179, 0xffff0000, v183
	v_lshlrev_b32_e32 v180, 16, v184
	v_and_b32_e32 v181, 0xffff0000, v184
	v_lshlrev_b32_e32 v182, 16, v185
	v_and_b32_e32 v183, 0xffff0000, v185
	v_lshlrev_b32_e32 v184, 16, v186
	v_and_b32_e32 v185, 0xffff0000, v186
	v_lshlrev_b32_e32 v186, 16, v187
	v_and_b32_e32 v187, 0xffff0000, v187
	v_pk_fma_f32 v[120:121], v[120:121], v[132:133], v[194:195]
	v_pk_fma_f32 v[104:105], v[104:105], v[128:129], v[198:199]
	v_pk_fma_f32 v[118:119], v[118:119], v[138:139], v[174:175]
	v_pk_fma_f32 v[116:117], v[116:117], v[136:137], v[172:173]
	v_pk_fma_f32 v[110:111], v[110:111], v[134:135], v[178:179]
	v_pk_fma_f32 v[108:109], v[108:109], v[132:133], v[176:177]
	v_pk_fma_f32 v[102:103], v[102:103], v[142:143], v[182:183]
	v_pk_fma_f32 v[100:101], v[100:101], v[140:141], v[180:181]
	v_pk_fma_f32 v[98:99], v[98:99], v[130:131], v[186:187]
	v_pk_fma_f32 v[96:97], v[96:97], v[128:129], v[184:185]
	global_store_dwordx4 v[190:191], v[124:127], off
	global_store_dwordx4 v[190:191], v[120:123], off offset:16
	global_store_dwordx4 v[190:191], v[112:115], off offset:512
	global_store_dwordx4 v[190:191], v[104:107], off offset:528
	global_store_dwordx4 v[188:189], v[116:119], off
	global_store_dwordx4 v[188:189], v[108:111], off offset:16
	global_store_dwordx4 v[188:189], v[100:103], off offset:512
	global_store_dwordx4 v[188:189], v[96:99], off offset:528
	v_or_b32_e32 v112, 32, v164
	v_or_b32_e32 v114, 48, v164
	v_ashrrev_i32_e32 v113, 31, v112
	v_ashrrev_i32_e32 v115, 31, v114
	v_lshlrev_b64 v[96:97], 11, v[112:113]
	v_lshlrev_b64 v[104:105], 11, v[114:115]
	v_lshl_add_u64 v[100:101], v[162:163], 0, v[96:97]
	v_lshl_add_u64 v[108:109], v[162:163], 0, v[104:105]
	v_lshlrev_b64 v[112:113], 12, v[112:113]
	v_lshlrev_b64 v[114:115], 12, v[114:115]
	v_lshl_add_u64 v[112:113], s[82:83], 0, v[112:113]
	v_lshl_add_u64 v[114:115], s[82:83], 0, v[114:115]
	v_lshl_add_u64 v[112:113], v[112:113], 0, v[160:161]
	v_add_u32_e32 v116, 0x80, v164
	v_lshl_add_u64 v[114:115], v[114:115], 0, v[160:161]
	v_ashrrev_i32_e32 v117, 31, v116
	v_lshlrev_b64 v[118:119], 11, v[116:117]
	v_lshl_add_u64 v[118:119], v[162:163], 0, v[118:119]
	v_lshlrev_b32_e32 v120, 16, v200
	v_and_b32_e32 v121, 0xffff0000, v200
	v_lshlrev_b32_e32 v200, 16, v201
	v_and_b32_e32 v201, 0xffff0000, v201
	v_lshlrev_b32_e32 v174, 16, v210
	v_and_b32_e32 v175, 0xffff0000, v210
	v_lshlrev_b32_e32 v122, 16, v202
	v_and_b32_e32 v123, 0xffff0000, v202
	v_lshlrev_b32_e32 v202, 16, v203
	v_and_b32_e32 v203, 0xffff0000, v203
	v_lshlrev_b32_e32 v124, 16, v204
	v_and_b32_e32 v125, 0xffff0000, v204
	v_lshlrev_b32_e32 v204, 16, v205
	v_and_b32_e32 v205, 0xffff0000, v205
	v_lshlrev_b32_e32 v126, 16, v206
	v_and_b32_e32 v127, 0xffff0000, v206
	v_lshlrev_b32_e32 v206, 16, v207
	v_and_b32_e32 v207, 0xffff0000, v207
	v_lshlrev_b32_e32 v172, 16, v208
	v_and_b32_e32 v173, 0xffff0000, v208
	v_lshlrev_b32_e32 v208, 16, v209
	v_and_b32_e32 v209, 0xffff0000, v209
	v_lshlrev_b32_e32 v210, 16, v211
	v_and_b32_e32 v211, 0xffff0000, v211
	v_lshlrev_b32_e32 v176, 16, v212
	v_and_b32_e32 v177, 0xffff0000, v212
	v_lshlrev_b32_e32 v212, 16, v213
	v_and_b32_e32 v213, 0xffff0000, v213
	v_lshlrev_b32_e32 v178, 16, v214
	v_and_b32_e32 v179, 0xffff0000, v214
	v_lshlrev_b32_e32 v214, 16, v215
	v_and_b32_e32 v215, 0xffff0000, v215
	v_pk_fma_f32 v[94:95], v[94:95], v[138:139], v[200:201]
	v_pk_fma_f32 v[92:93], v[92:93], v[136:137], v[120:121]
	v_pk_fma_f32 v[80:81], v[80:81], v[132:133], v[174:175]
	v_pk_fma_f32 v[90:91], v[90:91], v[134:135], v[202:203]
	v_pk_fma_f32 v[88:89], v[88:89], v[132:133], v[122:123]
	v_pk_fma_f32 v[78:79], v[78:79], v[142:143], v[204:205]
	v_pk_fma_f32 v[76:77], v[76:77], v[140:141], v[124:125]
	v_pk_fma_f32 v[74:75], v[74:75], v[130:131], v[206:207]
	v_pk_fma_f32 v[72:73], v[72:73], v[128:129], v[126:127]
	v_pk_fma_f32 v[86:87], v[86:87], v[138:139], v[208:209]
	v_pk_fma_f32 v[84:85], v[84:85], v[136:137], v[172:173]
	v_pk_fma_f32 v[82:83], v[82:83], v[134:135], v[210:211]
	v_pk_fma_f32 v[70:71], v[70:71], v[142:143], v[212:213]
	v_pk_fma_f32 v[68:69], v[68:69], v[140:141], v[176:177]
	v_pk_fma_f32 v[66:67], v[66:67], v[130:131], v[214:215]
	v_pk_fma_f32 v[64:65], v[64:65], v[128:129], v[178:179]
	s_mov_b32 s98, 0x50000
	s_mov_b32 s99, 0
	v_lshl_add_u64 v[248:249], s[98:99], 0, v[252:253]
	global_load_dwordx4 v[200:203], v[248:249], off nt
	global_load_dwordx4 v[204:207], v[248:249], off offset:256 nt
	s_nop 1
	s_mov_b32 s98, 0x58000
	s_mov_b32 s99, 0
	v_lshl_add_u64 v[248:249], s[98:99], 0, v[252:253]
	global_load_dwordx4 v[208:211], v[248:249], off nt
	global_load_dwordx4 v[212:215], v[248:249], off offset:256 nt
	s_nop 1
	global_store_dwordx4 v[112:113], v[92:95], off
	global_store_dwordx4 v[112:113], v[88:91], off offset:16
	global_store_dwordx4 v[112:113], v[76:79], off offset:512
	global_store_dwordx4 v[112:113], v[72:75], off offset:528
	global_store_dwordx4 v[114:115], v[84:87], off
	global_store_dwordx4 v[114:115], v[80:83], off offset:16
	global_store_dwordx4 v[114:115], v[68:71], off offset:512
	global_store_dwordx4 v[114:115], v[64:67], off offset:528
	v_add_u32_e32 v80, 0x90, v164
	v_ashrrev_i32_e32 v81, 31, v80
	v_lshlrev_b64 v[72:73], 11, v[80:81]
	v_lshl_add_u64 v[76:77], v[162:163], 0, v[72:73]
	v_lshlrev_b64 v[84:85], 12, v[116:117]
	v_lshlrev_b64 v[80:81], 12, v[80:81]
	v_lshl_add_u64 v[84:85], s[82:83], 0, v[84:85]
	v_lshl_add_u64 v[80:81], s[82:83], 0, v[80:81]
	v_lshl_add_u64 v[84:85], v[84:85], 0, v[160:161]
	v_add_u32_e32 v82, 0xa0, v164
	v_lshl_add_u64 v[80:81], v[80:81], 0, v[160:161]
	v_ashrrev_i32_e32 v83, 31, v82
	v_lshlrev_b64 v[86:87], 11, v[82:83]
	v_lshl_add_u64 v[86:87], v[162:163], 0, v[86:87]
	v_lshlrev_b32_e32 v88, 16, v230
	v_and_b32_e32 v89, 0xffff0000, v230
	v_lshlrev_b32_e32 v230, 16, v231
	v_and_b32_e32 v231, 0xffff0000, v231
	v_lshlrev_b32_e32 v98, 16, v240
	v_and_b32_e32 v99, 0xffff0000, v240
	v_lshlrev_b32_e32 v90, 16, v232
	v_and_b32_e32 v91, 0xffff0000, v232
	v_lshlrev_b32_e32 v232, 16, v233
	v_and_b32_e32 v233, 0xffff0000, v233
	v_lshlrev_b32_e32 v92, 16, v234
	v_and_b32_e32 v93, 0xffff0000, v234
	v_lshlrev_b32_e32 v234, 16, v235
	v_and_b32_e32 v235, 0xffff0000, v235
	v_lshlrev_b32_e32 v94, 16, v236
	v_and_b32_e32 v95, 0xffff0000, v236
	v_lshlrev_b32_e32 v236, 16, v237
	v_and_b32_e32 v237, 0xffff0000, v237
	v_lshlrev_b32_e32 v96, 16, v238
	v_and_b32_e32 v97, 0xffff0000, v238
	v_lshlrev_b32_e32 v238, 16, v239
	v_and_b32_e32 v239, 0xffff0000, v239
	v_lshlrev_b32_e32 v240, 16, v241
	v_and_b32_e32 v241, 0xffff0000, v241
	v_lshlrev_b32_e32 v100, 16, v244
	v_and_b32_e32 v101, 0xffff0000, v244
	v_lshlrev_b32_e32 v244, 16, v245
	v_and_b32_e32 v245, 0xffff0000, v245
	v_lshlrev_b32_e32 v102, 16, v246
	v_and_b32_e32 v103, 0xffff0000, v246
	v_lshlrev_b32_e32 v246, 16, v247
	v_and_b32_e32 v247, 0xffff0000, v247
	v_pk_fma_f32 v[62:63], v[62:63], v[138:139], v[230:231]
	v_pk_fma_f32 v[60:61], v[60:61], v[136:137], v[88:89]
	v_pk_fma_f32 v[48:49], v[48:49], v[132:133], v[98:99]
	v_pk_fma_f32 v[58:59], v[58:59], v[134:135], v[232:233]
	v_pk_fma_f32 v[56:57], v[56:57], v[132:133], v[90:91]
	v_pk_fma_f32 v[46:47], v[46:47], v[142:143], v[234:235]
	v_pk_fma_f32 v[44:45], v[44:45], v[140:141], v[92:93]
	v_pk_fma_f32 v[42:43], v[42:43], v[130:131], v[236:237]
	v_pk_fma_f32 v[40:41], v[40:41], v[128:129], v[94:95]
	v_pk_fma_f32 v[54:55], v[54:55], v[138:139], v[238:239]
	v_pk_fma_f32 v[52:53], v[52:53], v[136:137], v[96:97]
	v_pk_fma_f32 v[50:51], v[50:51], v[134:135], v[240:241]
	v_pk_fma_f32 v[38:39], v[38:39], v[142:143], v[244:245]
	v_pk_fma_f32 v[36:37], v[36:37], v[140:141], v[100:101]
	v_pk_fma_f32 v[34:35], v[34:35], v[130:131], v[246:247]
	v_pk_fma_f32 v[32:33], v[32:33], v[128:129], v[102:103]
	global_store_dwordx4 v[84:85], v[60:63], off
	global_store_dwordx4 v[84:85], v[56:59], off offset:16
	global_store_dwordx4 v[84:85], v[44:47], off offset:512
	global_store_dwordx4 v[84:85], v[40:43], off offset:528
	global_store_dwordx4 v[80:81], v[52:55], off
	global_store_dwordx4 v[80:81], v[48:51], off offset:16
	global_store_dwordx4 v[80:81], v[36:39], off offset:512
	global_store_dwordx4 v[80:81], v[32:35], off offset:528
	v_add_u32_e32 v48, 0xb0, v164
	v_ashrrev_i32_e32 v49, 31, v48
	v_lshlrev_b64 v[40:41], 11, v[48:49]
	v_lshl_add_u64 v[50:51], v[162:163], 0, v[40:41]
	v_lshlrev_b64 v[50:51], 12, v[82:83]
	v_lshlrev_b64 v[48:49], 12, v[48:49]
	v_lshl_add_u64 v[50:51], s[82:83], 0, v[50:51]
	v_lshl_add_u64 v[48:49], s[82:83], 0, v[48:49]
	v_lshl_add_u64 v[50:51], v[50:51], 0, v[160:161]
	v_lshl_add_u64 v[48:49], v[48:49], 0, v[160:161]
	s_waitcnt vmcnt(16)
	v_lshlrev_b32_e32 v52, 16, v200
	v_and_b32_e32 v53, 0xffff0000, v200
	v_lshlrev_b32_e32 v200, 16, v201
	v_and_b32_e32 v201, 0xffff0000, v201
	v_lshlrev_b32_e32 v54, 16, v202
	v_and_b32_e32 v55, 0xffff0000, v202
	v_lshlrev_b32_e32 v202, 16, v203
	v_and_b32_e32 v203, 0xffff0000, v203
	v_lshlrev_b32_e32 v56, 16, v204
	v_and_b32_e32 v57, 0xffff0000, v204
	v_lshlrev_b32_e32 v204, 16, v205
	v_and_b32_e32 v205, 0xffff0000, v205
	v_lshlrev_b32_e32 v58, 16, v206
	v_and_b32_e32 v59, 0xffff0000, v206
	v_lshlrev_b32_e32 v206, 16, v207
	v_and_b32_e32 v207, 0xffff0000, v207
	v_lshlrev_b32_e32 v60, 16, v208
	v_and_b32_e32 v61, 0xffff0000, v208
	v_lshlrev_b32_e32 v208, 16, v209
	v_and_b32_e32 v209, 0xffff0000, v209
	v_lshlrev_b32_e32 v62, 16, v210
	v_and_b32_e32 v63, 0xffff0000, v210
	v_lshlrev_b32_e32 v210, 16, v211
	v_and_b32_e32 v211, 0xffff0000, v211
	v_lshlrev_b32_e32 v64, 16, v212
	v_and_b32_e32 v65, 0xffff0000, v212
	v_lshlrev_b32_e32 v212, 16, v213
	v_and_b32_e32 v213, 0xffff0000, v213
	v_lshlrev_b32_e32 v66, 16, v214
	v_and_b32_e32 v67, 0xffff0000, v214
	v_lshlrev_b32_e32 v214, 16, v215
	v_and_b32_e32 v215, 0xffff0000, v215
	v_pk_fma_f32 v[30:31], v[30:31], v[138:139], v[200:201]
	v_pk_fma_f32 v[28:29], v[28:29], v[136:137], v[52:53]
	v_pk_fma_f32 v[26:27], v[26:27], v[134:135], v[202:203]
	v_pk_fma_f32 v[24:25], v[24:25], v[132:133], v[54:55]
	v_pk_fma_f32 v[14:15], v[14:15], v[142:143], v[204:205]
	v_pk_fma_f32 v[12:13], v[12:13], v[140:141], v[56:57]
	v_pk_fma_f32 v[10:11], v[10:11], v[130:131], v[206:207]
	v_pk_fma_f32 v[8:9], v[8:9], v[128:129], v[58:59]
	v_pk_fma_f32 v[22:23], v[22:23], v[138:139], v[208:209]
	v_pk_fma_f32 v[20:21], v[20:21], v[136:137], v[60:61]
	v_pk_fma_f32 v[18:19], v[18:19], v[134:135], v[210:211]
	v_pk_fma_f32 v[16:17], v[16:17], v[132:133], v[62:63]
	v_pk_fma_f32 v[6:7], v[6:7], v[142:143], v[212:213]
	v_pk_fma_f32 v[4:5], v[4:5], v[140:141], v[64:65]
	v_pk_fma_f32 v[2:3], v[2:3], v[130:131], v[214:215]
	v_pk_fma_f32 v[0:1], v[0:1], v[128:129], v[66:67]
	global_store_dwordx4 v[50:51], v[28:31], off
	global_store_dwordx4 v[50:51], v[24:27], off offset:16
	global_store_dwordx4 v[50:51], v[12:15], off offset:512
	global_store_dwordx4 v[50:51], v[8:11], off offset:528
	global_store_dwordx4 v[48:49], v[20:23], off
	global_store_dwordx4 v[48:49], v[16:19], off offset:16
	global_store_dwordx4 v[48:49], v[4:7], off offset:512
	global_store_dwordx4 v[48:49], v[0:3], off offset:528
	s_cbranch_vccnz .LBB0_1451
	s_andn2_b64 vcc, exec, s[6:7]
	s_cbranch_vccnz .LBB0_1450
	s_barrier
	s_branch .LBB0_1450
